# split scan/attention, attention tiles throttled harder (s_sleep 127+45 per tile, attention spans ~175 us)
# speedup vs baseline: 1.0135x; 1.0135x over previous
; #define LAS __attribute__((address_space(3)))
; __device__ __forceinline__ void phase_attn(const Params& p, int l, LAS unsigned char* ldsb) {
;     ...
;         for (int rt = 0; rt < 4; ++rt) {
;             const int q0 = (wid & 1) * 64 + rt * 16, kstart = q0 < 96 ? q0 : 96;
;             bf16x8 qa0, qa1; { const bf16_t* qp = QKV + (size_t)(tokc + q0 + fr) * 768 + hq * 64 + fq * 8; qa0 = *(const bf16x8*)qp; qa1 = *(const bf16x8*)(qp + 32); }
;             f32x4 S[10];
; #pragma unroll
;             for (int kt = 0; kt < 10; ++kt) {
;                 LAS const bf16_t* kp = Ks + (kstart + kt * 16 + fr) * 72 + fq * 8;
;                 const bf16x8 k0 = *(LAS const bf16x8*)kp, k1 = *(LAS const bf16x8*)(kp + 32);
;                 f32x4 z = (f32x4){0.f, 0.f, 0.f, 0.f};
;                 z = __builtin_amdgcn_mfma_f32_16x16x32_bf16(qa0, k0, z, 0, 0, 0);
;                 z = __builtin_amdgcn_mfma_f32_16x16x32_bf16(qa1, k1, z, 0, 0, 0);
;                 S[kt] = z;
;             }
;             float mx[4] = {-INFINITY, -INFINITY, -INFINITY, -INFINITY};
; #pragma unroll
;             for (int kt = 0; kt < 10; ++kt)
; #pragma unroll
;                 for (int j = 0; j < 4; ++j) {
;                     const int key = kstart + kt * 16 + fr, dist = q0 + 4 * fq + j + 128 - key;
;                     const bool ok = (dist >= 0) && (dist < 128) && (n > 0 || key >= 128);
;                     const float s = ok ? (S[kt][j] * 0.125f + biasL[hl * 128 + (dist & 127)]) : -INFINITY;
;                     S[kt][j] = s; mx[j] = fmaxf(mx[j], s);
;                 }
.Lat_rt:
	s_sleep 127
	s_sleep 45
	s_and_b32 s51, s48, 3
	s_lshl_b32 s51, s51, 4
	s_lshl_b32 s49, s46, 6
	s_add_u32 s49, s49, s51
	s_min_u32 s50, s49, 96
	s_lshr_b32 s51, s48, 2
	s_lshl_b32 s81, s51, 13
	s_add_u32 s81, s81, s32
	s_add_u32 s81, s81, s49
	s_lshl_b32 s81, s81, 10
	s_lshl_b32 s84, s47, 7
	s_add_u32 s81, s81, s84
	s_add_u32 s81, s81, 0x7000000
	s_add_u32 s42, s74, s81
	s_addc_u32 s43, s75, 0
	s_lshl_b32 s51, s51, 16
	s_lshl_b32 s81, s50, 7
	s_add_u32 s51, s51, s81
	v_add_u32_e32 v15, s51, v13
	v_add_u32_e32 v16, s51, v14
	v_add_u32_e32 v23, s51, v19
	v_add_u32_e32 v24, s51, v20
	v_add_u32_e32 v25, s51, v21
	v_add_u32_e32 v26, s51, v22
	s_sub_u32 s81, s49, s50
	s_sub_u32 s81, 32, s81
	s_lshl_b32 s81, s81, 2
	v_add_u32_e32 v18, s81, v17
	s_sub_u32 s84, 128, s50
	s_lshr_b32 s84, s84, 4
	s_cmp_eq_u32 s13, 0
	s_cselect_b32 s84, s84, 0
	ds_read_b128 v[104:107], v18 offset:0
	ds_read_b128 v[108:111], v18 offset:64
	ds_read_b128 v[112:115], v18 offset:128
	ds_read_b128 v[116:119], v18 offset:192
	ds_read_b128 v[120:123], v18 offset:256
	ds_read_b128 v[124:127], v18 offset:320
	ds_read_b128 v[128:131], v18 offset:384
	ds_read_b128 v[132:135], v18 offset:448
	ds_read_b128 v[136:139], v18 offset:512
	ds_read_b128 v[140:143], v18 offset:576
	ds_read_b128 v[48:51], v15 offset:0
	ds_read_b128 v[52:55], v16 offset:0
	ds_read_b128 v[56:59], v15 offset:2048
	ds_read_b128 v[60:63], v16 offset:2048
	s_waitcnt lgkmcnt(2)
	v_mfma_f32_16x16x32_bf16 v[64:67], v[48:51], v[40:43], 0
	v_mfma_f32_16x16x32_bf16 v[64:67], v[52:55], v[44:47], v[64:67]
	ds_read_b128 v[48:51], v15 offset:4096
	ds_read_b128 v[52:55], v16 offset:4096
	s_waitcnt lgkmcnt(2)
	v_mfma_f32_16x16x32_bf16 v[68:71], v[56:59], v[40:43], 0
	v_mfma_f32_16x16x32_bf16 v[68:71], v[60:63], v[44:47], v[68:71]
	ds_read_b128 v[56:59], v15 offset:6144
	ds_read_b128 v[60:63], v16 offset:6144
	s_waitcnt lgkmcnt(2)
	v_mfma_f32_16x16x32_bf16 v[72:75], v[48:51], v[40:43], 0
	v_mfma_f32_16x16x32_bf16 v[72:75], v[52:55], v[44:47], v[72:75]
	ds_read_b128 v[48:51], v15 offset:8192
	ds_read_b128 v[52:55], v16 offset:8192
	s_waitcnt lgkmcnt(2)
	v_mfma_f32_16x16x32_bf16 v[76:79], v[56:59], v[40:43], 0
	v_mfma_f32_16x16x32_bf16 v[76:79], v[60:63], v[44:47], v[76:79]
	ds_read_b128 v[56:59], v15 offset:10240
	ds_read_b128 v[60:63], v16 offset:10240
	s_waitcnt lgkmcnt(2)
	v_mfma_f32_16x16x32_bf16 v[80:83], v[48:51], v[40:43], 0
	v_mfma_f32_16x16x32_bf16 v[80:83], v[52:55], v[44:47], v[80:83]
	ds_read_b128 v[48:51], v15 offset:12288
	ds_read_b128 v[52:55], v16 offset:12288
	s_waitcnt lgkmcnt(2)
	v_mfma_f32_16x16x32_bf16 v[84:87], v[56:59], v[40:43], 0
	v_mfma_f32_16x16x32_bf16 v[84:87], v[60:63], v[44:47], v[84:87]
	ds_read_b128 v[56:59], v15 offset:14336
	ds_read_b128 v[60:63], v16 offset:14336
	s_waitcnt lgkmcnt(2)
	v_mfma_f32_16x16x32_bf16 v[88:91], v[48:51], v[40:43], 0
	v_mfma_f32_16x16x32_bf16 v[88:91], v[52:55], v[44:47], v[88:91]
	ds_read_b128 v[48:51], v15 offset:16384
	ds_read_b128 v[52:55], v16 offset:16384
	s_waitcnt lgkmcnt(2)
	v_mfma_f32_16x16x32_bf16 v[92:95], v[56:59], v[40:43], 0
	v_mfma_f32_16x16x32_bf16 v[92:95], v[60:63], v[44:47], v[92:95]
	ds_read_b128 v[56:59], v15 offset:18432
	ds_read_b128 v[60:63], v16 offset:18432
	s_waitcnt lgkmcnt(2)
	v_mfma_f32_16x16x32_bf16 v[96:99], v[48:51], v[40:43], 0
	v_mfma_f32_16x16x32_bf16 v[96:99], v[52:55], v[44:47], v[96:99]
	s_waitcnt lgkmcnt(0)
	v_mfma_f32_16x16x32_bf16 v[100:103], v[56:59], v[40:43], 0
	v_mfma_f32_16x16x32_bf16 v[100:103], v[60:63], v[44:47], v[100:103]
	s_add_u32 s51, s48, 1
	s_min_u32 s51, s51, 7
	s_lshr_b32 s81, s51, 2
	s_lshl_b32 s81, s81, 13
	s_and_b32 s51, s51, 3
	s_lshl_b32 s51, s51, 4
	s_add_u32 s81, s81, s51
	s_lshl_b32 s51, s46, 6
	s_add_u32 s81, s81, s51
	s_add_u32 s81, s81, s32
	s_mul_i32 s81, s81, 1536
	s_lshl_b32 s51, s47, 7
	s_add_u32 s81, s81, s51
	s_add_u32 s40, s74, s81
	s_addc_u32 s41, s75, 0
	global_load_dwordx4 v[40:43], v27, s[40:41]
	global_load_dwordx4 v[44:47], v27, s[40:41] offset:64
	v_fma_f32 v64, v64, s82, v104
	v_fma_f32 v65, v65, s82, v105
	v_fma_f32 v66, v66, s82, v106
	v_fma_f32 v67, v67, s82, v107
	v_fma_f32 v68, v68, s82, v108
	v_fma_f32 v69, v69, s82, v109
	v_fma_f32 v70, v70, s82, v110
	v_fma_f32 v71, v71, s82, v111
	v_fma_f32 v72, v72, s82, v112
	v_fma_f32 v73, v73, s82, v113
	v_fma_f32 v74, v74, s82, v114
	v_fma_f32 v75, v75, s82, v115
	v_fma_f32 v76, v76, s82, v116
	v_fma_f32 v77, v77, s82, v117
	v_fma_f32 v78, v78, s82, v118
	v_fma_f32 v79, v79, s82, v119
	v_fma_f32 v80, v80, s82, v120
	v_fma_f32 v81, v81, s82, v121
	v_fma_f32 v82, v82, s82, v122
	v_fma_f32 v83, v83, s82, v123
	v_fma_f32 v84, v84, s82, v124
	v_fma_f32 v85, v85, s82, v125
	v_fma_f32 v86, v86, s82, v126
	v_fma_f32 v87, v87, s82, v127
	v_fma_f32 v88, v88, s82, v128
	v_fma_f32 v89, v89, s82, v129
	v_fma_f32 v90, v90, s82, v130
	v_fma_f32 v91, v91, s82, v131
	v_fma_f32 v92, v92, s82, v132
	v_fma_f32 v93, v93, s82, v133
	v_fma_f32 v94, v94, s82, v134
	v_fma_f32 v95, v95, s82, v135
	v_fma_f32 v96, v96, s82, v136
	v_fma_f32 v97, v97, s82, v137
	v_fma_f32 v98, v98, s82, v138
	v_fma_f32 v99, v99, s82, v139
	v_fma_f32 v100, v100, s82, v140
	v_fma_f32 v101, v101, s82, v141
	v_fma_f32 v102, v102, s82, v142
	v_fma_f32 v103, v103, s82, v143
	s_cmp_eq_u32 s84, 0
	s_nop 0
	s_cbranch_scc1 .Lat_nomask
	s_cmp_gt_u32 s84, 0
	s_cselect_b32 s86, 0xff800000, 0
	v_add_f32_e32 v64, s86, v64
	v_add_f32_e32 v65, s86, v65
	v_add_f32_e32 v66, s86, v66
	v_add_f32_e32 v67, s86, v67
	s_cmp_gt_u32 s84, 1
	s_cselect_b32 s86, 0xff800000, 0
	v_add_f32_e32 v68, s86, v68
	v_add_f32_e32 v69, s86, v69
	v_add_f32_e32 v70, s86, v70
	v_add_f32_e32 v71, s86, v71
	s_cmp_gt_u32 s84, 2
	s_cselect_b32 s86, 0xff800000, 0
	v_add_f32_e32 v72, s86, v72
	v_add_f32_e32 v73, s86, v73
	v_add_f32_e32 v74, s86, v74
	v_add_f32_e32 v75, s86, v75
	s_cmp_gt_u32 s84, 3
	s_cselect_b32 s86, 0xff800000, 0
	v_add_f32_e32 v76, s86, v76
	v_add_f32_e32 v77, s86, v77
	v_add_f32_e32 v78, s86, v78
	v_add_f32_e32 v79, s86, v79
	s_cmp_gt_u32 s84, 4
	s_cselect_b32 s86, 0xff800000, 0
	v_add_f32_e32 v80, s86, v80
	v_add_f32_e32 v81, s86, v81
	v_add_f32_e32 v82, s86, v82
	v_add_f32_e32 v83, s86, v83
	s_cmp_gt_u32 s84, 5
	s_cselect_b32 s86, 0xff800000, 0
	v_add_f32_e32 v84, s86, v84
	v_add_f32_e32 v85, s86, v85
	v_add_f32_e32 v86, s86, v86
	v_add_f32_e32 v87, s86, v87
	s_cmp_gt_u32 s84, 6
	s_cselect_b32 s86, 0xff800000, 0
	v_add_f32_e32 v88, s86, v88
	v_add_f32_e32 v89, s86, v89
	v_add_f32_e32 v90, s86, v90
	v_add_f32_e32 v91, s86, v91
	s_cmp_gt_u32 s84, 7
	s_cselect_b32 s86, 0xff800000, 0
	v_add_f32_e32 v92, s86, v92
	v_add_f32_e32 v93, s86, v93
	v_add_f32_e32 v94, s86, v94
	v_add_f32_e32 v95, s86, v95
	s_nop 1
